# pooling window sum 4 rows in flight with exhausted lanes masked off the prefetch loads; final grid barrier of the last layer skipped (early s_endpgm)
# speedup vs baseline: 1.0059x; 1.0027x over previous
; __device__ __forceinline__ float lo16(unsigned w) { return __uint_as_float(w << 16); }
; __device__ __forceinline__ float hi16(unsigned w) { return __uint_as_float(w & 0xffff0000u); }
; __device__ __forceinline__ void prep_pool_item(const KPD& kp, int l, int sc, unsigned char* lds, int tid, int lane, int wave) {
;     ...
;       for (int j = lo; j < hi; ++j) { const bf16* up = P + (size_t)(rowbase + j - s0) * INP + cb;
; #pragma unroll
;           for (int q = 0; q < 4; ++q) { const v4u v = *(const v4u*)(up + 8 * q);
;               acc[8 * q] += lo16(v.x); acc[8 * q + 1] += hi16(v.x); acc[8 * q + 2] += lo16(v.y); acc[8 * q + 3] += hi16(v.y); acc[8 * q + 4] += lo16(v.z); acc[8 * q + 5] += hi16(v.z); acc[8 * q + 6] += lo16(v.w); acc[8 * q + 7] += hi16(v.w); } }
.LBB0_298:
	s_mov_b64 s[2:3], exec
	v_mov_b32_e32 v157, 0
	v_mov_b32_e32 v158, 0x1200
	v_mov_b32_e32 v178, v61
	s_ff1_i32_b64 s28, s[2:3]
	s_lshl_b64 s[100:101], 1, s28
	global_load_dwordx4 v[62:65], v[58:59], off
	global_load_dwordx4 v[66:69], v[58:59], off offset:-16
	global_load_dwordx4 v[96:99], v[58:59], off offset:-32
	global_load_dwordx4 v[100:103], v[58:59], off offset:-48
	v_add_u32_e32 v178, 1, v178
	v_cmp_lt_i32_e32 vcc, v178, v60
	s_nop 1
	v_cndmask_b32_e32 v156, v157, v158, vcc
	v_lshl_add_u64 v[58:59], v[58:59], 0, v[156:157]
	s_and_b64 s[28:29], s[2:3], vcc
	s_or_b64 s[28:29], s[28:29], s[100:101]
	s_mov_b64 exec, s[28:29]
	global_load_dwordx4 v[106:109], v[58:59], off
	global_load_dwordx4 v[110:113], v[58:59], off offset:-16
	global_load_dwordx4 v[114:117], v[58:59], off offset:-32
	global_load_dwordx4 v[150:153], v[58:59], off offset:-48
	s_mov_b64 exec, s[2:3]
	v_add_u32_e32 v178, 1, v178
	v_cmp_lt_i32_e32 vcc, v178, v60
	s_nop 1
	v_cndmask_b32_e32 v156, v157, v158, vcc
	v_lshl_add_u64 v[58:59], v[58:59], 0, v[156:157]
	s_and_b64 s[28:29], s[2:3], vcc
	s_or_b64 s[28:29], s[28:29], s[100:101]
	s_mov_b64 exec, s[28:29]
	global_load_dwordx4 v[160:163], v[58:59], off
	global_load_dwordx4 v[164:167], v[58:59], off offset:-16
	global_load_dwordx4 v[168:171], v[58:59], off offset:-32
	global_load_dwordx4 v[172:175], v[58:59], off offset:-48
	s_mov_b64 exec, s[2:3]
.Lpool4_loop:
	v_add_u32_e32 v178, 1, v178
	v_cmp_lt_i32_e32 vcc, v178, v60
	s_nop 1
	v_cndmask_b32_e32 v156, v157, v158, vcc
	v_lshl_add_u64 v[58:59], v[58:59], 0, v[156:157]
	s_and_b64 s[28:29], s[2:3], vcc
	s_or_b64 s[28:29], s[28:29], s[100:101]
	s_mov_b64 exec, s[28:29]
	global_load_dwordx4 v[186:189], v[58:59], off
	global_load_dwordx4 v[190:193], v[58:59], off offset:-16
	global_load_dwordx4 v[194:197], v[58:59], off offset:-32
	global_load_dwordx4 v[198:201], v[58:59], off offset:-48
	s_mov_b64 exec, s[2:3]
	s_waitcnt vmcnt(12)
	v_cmp_lt_i32_e32 vcc, v61, v60
	s_and_b64 exec, s[2:3], vcc
	s_cbranch_scc0 .Lpool4_done
	v_and_b32_e32 v104, 0xffff0000, v100
	v_lshlrev_b32_e32 v105, 16, v100
	v_and_b32_e32 v100, 0xffff0000, v101
	v_lshlrev_b32_e32 v101, 16, v101
	v_pk_add_f32 v[54:55], v[54:55], v[100:101]
	v_and_b32_e32 v100, 0xffff0000, v102
	v_lshlrev_b32_e32 v101, 16, v102
	v_pk_add_f32 v[52:53], v[52:53], v[100:101]
	v_and_b32_e32 v100, 0xffff0000, v103
	v_lshlrev_b32_e32 v101, 16, v103
	v_pk_add_f32 v[50:51], v[50:51], v[100:101]
	v_and_b32_e32 v100, 0xffff0000, v96
	v_lshlrev_b32_e32 v101, 16, v96
	v_and_b32_e32 v96, 0xffff0000, v97
	v_lshlrev_b32_e32 v97, 16, v97
	v_pk_add_f32 v[46:47], v[46:47], v[96:97]
	v_and_b32_e32 v96, 0xffff0000, v98
	v_lshlrev_b32_e32 v97, 16, v98
	v_pk_add_f32 v[44:45], v[44:45], v[96:97]
	v_and_b32_e32 v96, 0xffff0000, v99
	v_lshlrev_b32_e32 v97, 16, v99
	v_pk_add_f32 v[42:43], v[42:43], v[96:97]
	v_and_b32_e32 v96, 0xffff0000, v66
	v_lshlrev_b32_e32 v97, 16, v66
	v_and_b32_e32 v66, 0xffff0000, v67
	v_lshlrev_b32_e32 v67, 16, v67
	v_pk_add_f32 v[14:15], v[14:15], v[66:67]
	v_and_b32_e32 v66, 0xffff0000, v68
	v_lshlrev_b32_e32 v67, 16, v68
	v_pk_add_f32 v[12:13], v[12:13], v[66:67]
	v_and_b32_e32 v66, 0xffff0000, v69
	v_lshlrev_b32_e32 v67, 16, v69
	v_pk_add_f32 v[10:11], v[10:11], v[66:67]
	v_and_b32_e32 v66, 0xffff0000, v62
	v_lshlrev_b32_e32 v67, 16, v62
	v_and_b32_e32 v62, 0xffff0000, v63
	v_lshlrev_b32_e32 v63, 16, v63
	v_pk_add_f32 v[6:7], v[6:7], v[62:63]
	v_and_b32_e32 v62, 0xffff0000, v64
	v_lshlrev_b32_e32 v63, 16, v64
	v_pk_add_f32 v[4:5], v[4:5], v[62:63]
	v_and_b32_e32 v62, 0xffff0000, v65
	v_lshlrev_b32_e32 v63, 16, v65
	v_pk_add_f32 v[56:57], v[56:57], v[104:105]
	v_pk_add_f32 v[48:49], v[48:49], v[100:101]
	v_pk_add_f32 v[16:17], v[16:17], v[96:97]
	v_pk_add_f32 v[8:9], v[8:9], v[66:67]
	v_pk_add_f32 v[2:3], v[2:3], v[62:63]
	s_mov_b64 exec, s[2:3]
	v_add_u32_e32 v61, 1, v61
	v_add_u32_e32 v178, 1, v178
	v_cmp_lt_i32_e32 vcc, v178, v60
	s_nop 1
	v_cndmask_b32_e32 v156, v157, v158, vcc
	v_lshl_add_u64 v[58:59], v[58:59], 0, v[156:157]
	s_and_b64 s[28:29], s[2:3], vcc
	s_or_b64 s[28:29], s[28:29], s[100:101]
	s_mov_b64 exec, s[28:29]
	global_load_dwordx4 v[62:65], v[58:59], off
	global_load_dwordx4 v[66:69], v[58:59], off offset:-16
	global_load_dwordx4 v[96:99], v[58:59], off offset:-32
	global_load_dwordx4 v[100:103], v[58:59], off offset:-48
	s_mov_b64 exec, s[2:3]
	s_waitcnt vmcnt(12)
	v_cmp_lt_i32_e32 vcc, v61, v60
	s_and_b64 exec, s[2:3], vcc
	s_cbranch_scc0 .Lpool4_done
; __device__ __forceinline__ float lo16(unsigned w) { return __uint_as_float(w << 16); }
; __device__ __forceinline__ float hi16(unsigned w) { return __uint_as_float(w & 0xffff0000u); }
; __device__ __forceinline__ void prep_pool_item(const KPD& kp, int l, int sc, unsigned char* lds, int tid, int lane, int wave) {
;     ...
;       for (int j = lo; j < hi; ++j) { const bf16* up = P + (size_t)(rowbase + j - s0) * INP + cb;
; #pragma unroll
;           for (int q = 0; q < 4; ++q) { const v4u v = *(const v4u*)(up + 8 * q);
;               acc[8 * q] += lo16(v.x); acc[8 * q + 1] += hi16(v.x); acc[8 * q + 2] += lo16(v.y); acc[8 * q + 3] += hi16(v.y); acc[8 * q + 4] += lo16(v.z); acc[8 * q + 5] += hi16(v.z); acc[8 * q + 6] += lo16(v.w); acc[8 * q + 7] += hi16(v.w); } }
	v_and_b32_e32 v154, 0xffff0000, v150
	v_lshlrev_b32_e32 v155, 16, v150
	v_and_b32_e32 v150, 0xffff0000, v151
	v_lshlrev_b32_e32 v151, 16, v151
	v_pk_add_f32 v[54:55], v[54:55], v[150:151]
	v_and_b32_e32 v150, 0xffff0000, v152
	v_lshlrev_b32_e32 v151, 16, v152
	v_pk_add_f32 v[52:53], v[52:53], v[150:151]
	v_and_b32_e32 v150, 0xffff0000, v153
	v_lshlrev_b32_e32 v151, 16, v153
	v_pk_add_f32 v[50:51], v[50:51], v[150:151]
	v_and_b32_e32 v150, 0xffff0000, v114
	v_lshlrev_b32_e32 v151, 16, v114
	v_and_b32_e32 v114, 0xffff0000, v115
	v_lshlrev_b32_e32 v115, 16, v115
	v_pk_add_f32 v[46:47], v[46:47], v[114:115]
	v_and_b32_e32 v114, 0xffff0000, v116
	v_lshlrev_b32_e32 v115, 16, v116
	v_pk_add_f32 v[44:45], v[44:45], v[114:115]
	v_and_b32_e32 v114, 0xffff0000, v117
	v_lshlrev_b32_e32 v115, 16, v117
	v_pk_add_f32 v[42:43], v[42:43], v[114:115]
	v_and_b32_e32 v114, 0xffff0000, v110
	v_lshlrev_b32_e32 v115, 16, v110
	v_and_b32_e32 v110, 0xffff0000, v111
	v_lshlrev_b32_e32 v111, 16, v111
	v_pk_add_f32 v[14:15], v[14:15], v[110:111]
	v_and_b32_e32 v110, 0xffff0000, v112
	v_lshlrev_b32_e32 v111, 16, v112
	v_pk_add_f32 v[12:13], v[12:13], v[110:111]
	v_and_b32_e32 v110, 0xffff0000, v113
	v_lshlrev_b32_e32 v111, 16, v113
	v_pk_add_f32 v[10:11], v[10:11], v[110:111]
	v_and_b32_e32 v110, 0xffff0000, v106
	v_lshlrev_b32_e32 v111, 16, v106
	v_and_b32_e32 v106, 0xffff0000, v107
	v_lshlrev_b32_e32 v107, 16, v107
	v_pk_add_f32 v[6:7], v[6:7], v[106:107]
	v_and_b32_e32 v106, 0xffff0000, v108
	v_lshlrev_b32_e32 v107, 16, v108
	v_pk_add_f32 v[4:5], v[4:5], v[106:107]
	v_and_b32_e32 v106, 0xffff0000, v109
	v_lshlrev_b32_e32 v107, 16, v109
	v_pk_add_f32 v[56:57], v[56:57], v[154:155]
	v_pk_add_f32 v[48:49], v[48:49], v[150:151]
	v_pk_add_f32 v[16:17], v[16:17], v[114:115]
	v_pk_add_f32 v[8:9], v[8:9], v[110:111]
	v_pk_add_f32 v[2:3], v[2:3], v[106:107]
	s_mov_b64 exec, s[2:3]
	v_add_u32_e32 v61, 1, v61
	v_add_u32_e32 v178, 1, v178
	v_cmp_lt_i32_e32 vcc, v178, v60
	s_nop 1
	v_cndmask_b32_e32 v156, v157, v158, vcc
	v_lshl_add_u64 v[58:59], v[58:59], 0, v[156:157]
	s_and_b64 s[28:29], s[2:3], vcc
	s_or_b64 s[28:29], s[28:29], s[100:101]
	s_mov_b64 exec, s[28:29]
	global_load_dwordx4 v[106:109], v[58:59], off
	global_load_dwordx4 v[110:113], v[58:59], off offset:-16
	global_load_dwordx4 v[114:117], v[58:59], off offset:-32
	global_load_dwordx4 v[150:153], v[58:59], off offset:-48
	s_mov_b64 exec, s[2:3]
	s_waitcnt vmcnt(12)
	v_cmp_lt_i32_e32 vcc, v61, v60
	s_and_b64 exec, s[2:3], vcc
	s_cbranch_scc0 .Lpool4_done
	v_and_b32_e32 v176, 0xffff0000, v172
	v_lshlrev_b32_e32 v177, 16, v172
	v_and_b32_e32 v172, 0xffff0000, v173
	v_lshlrev_b32_e32 v173, 16, v173
	v_pk_add_f32 v[54:55], v[54:55], v[172:173]
	v_and_b32_e32 v172, 0xffff0000, v174
	v_lshlrev_b32_e32 v173, 16, v174
	v_pk_add_f32 v[52:53], v[52:53], v[172:173]
	v_and_b32_e32 v172, 0xffff0000, v175
	v_lshlrev_b32_e32 v173, 16, v175
	v_pk_add_f32 v[50:51], v[50:51], v[172:173]
	v_and_b32_e32 v172, 0xffff0000, v168
	v_lshlrev_b32_e32 v173, 16, v168
	v_and_b32_e32 v168, 0xffff0000, v169
	v_lshlrev_b32_e32 v169, 16, v169
	v_pk_add_f32 v[46:47], v[46:47], v[168:169]
	v_and_b32_e32 v168, 0xffff0000, v170
	v_lshlrev_b32_e32 v169, 16, v170
	v_pk_add_f32 v[44:45], v[44:45], v[168:169]
	v_and_b32_e32 v168, 0xffff0000, v171
	v_lshlrev_b32_e32 v169, 16, v171
	v_pk_add_f32 v[42:43], v[42:43], v[168:169]
	v_and_b32_e32 v168, 0xffff0000, v164
	v_lshlrev_b32_e32 v169, 16, v164
	v_and_b32_e32 v164, 0xffff0000, v165
	v_lshlrev_b32_e32 v165, 16, v165
	v_pk_add_f32 v[14:15], v[14:15], v[164:165]
	v_and_b32_e32 v164, 0xffff0000, v166
	v_lshlrev_b32_e32 v165, 16, v166
	v_pk_add_f32 v[12:13], v[12:13], v[164:165]
	v_and_b32_e32 v164, 0xffff0000, v167
	v_lshlrev_b32_e32 v165, 16, v167
	v_pk_add_f32 v[10:11], v[10:11], v[164:165]
	v_and_b32_e32 v164, 0xffff0000, v160
	v_lshlrev_b32_e32 v165, 16, v160
	v_and_b32_e32 v160, 0xffff0000, v161
	v_lshlrev_b32_e32 v161, 16, v161
	v_pk_add_f32 v[6:7], v[6:7], v[160:161]
	v_and_b32_e32 v160, 0xffff0000, v162
	v_lshlrev_b32_e32 v161, 16, v162
	v_pk_add_f32 v[4:5], v[4:5], v[160:161]
	v_and_b32_e32 v160, 0xffff0000, v163
	v_lshlrev_b32_e32 v161, 16, v163
	v_pk_add_f32 v[56:57], v[56:57], v[176:177]
	v_pk_add_f32 v[48:49], v[48:49], v[172:173]
	v_pk_add_f32 v[16:17], v[16:17], v[168:169]
	v_pk_add_f32 v[8:9], v[8:9], v[164:165]
	v_pk_add_f32 v[2:3], v[2:3], v[160:161]
	s_mov_b64 exec, s[2:3]
	v_add_u32_e32 v61, 1, v61
	v_add_u32_e32 v178, 1, v178
	v_cmp_lt_i32_e32 vcc, v178, v60
	s_nop 1
	v_cndmask_b32_e32 v156, v157, v158, vcc
	v_lshl_add_u64 v[58:59], v[58:59], 0, v[156:157]
	s_and_b64 s[28:29], s[2:3], vcc
	s_or_b64 s[28:29], s[28:29], s[100:101]
	s_mov_b64 exec, s[28:29]
	global_load_dwordx4 v[160:163], v[58:59], off
	global_load_dwordx4 v[164:167], v[58:59], off offset:-16
	global_load_dwordx4 v[168:171], v[58:59], off offset:-32
	global_load_dwordx4 v[172:175], v[58:59], off offset:-48
	s_mov_b64 exec, s[2:3]
	s_waitcnt vmcnt(12)
	v_cmp_lt_i32_e32 vcc, v61, v60
	s_and_b64 exec, s[2:3], vcc
	s_cbranch_scc0 .Lpool4_done
	v_and_b32_e32 v202, 0xffff0000, v198
	v_lshlrev_b32_e32 v203, 16, v198
	v_and_b32_e32 v198, 0xffff0000, v199
	v_lshlrev_b32_e32 v199, 16, v199
	v_pk_add_f32 v[54:55], v[54:55], v[198:199]
	v_and_b32_e32 v198, 0xffff0000, v200
	v_lshlrev_b32_e32 v199, 16, v200
	v_pk_add_f32 v[52:53], v[52:53], v[198:199]
	v_and_b32_e32 v198, 0xffff0000, v201
	v_lshlrev_b32_e32 v199, 16, v201
	v_pk_add_f32 v[50:51], v[50:51], v[198:199]
	v_and_b32_e32 v198, 0xffff0000, v194
	v_lshlrev_b32_e32 v199, 16, v194
	v_and_b32_e32 v194, 0xffff0000, v195
	v_lshlrev_b32_e32 v195, 16, v195
	v_pk_add_f32 v[46:47], v[46:47], v[194:195]
	v_and_b32_e32 v194, 0xffff0000, v196
	v_lshlrev_b32_e32 v195, 16, v196
	v_pk_add_f32 v[44:45], v[44:45], v[194:195]
	v_and_b32_e32 v194, 0xffff0000, v197
	v_lshlrev_b32_e32 v195, 16, v197
	v_pk_add_f32 v[42:43], v[42:43], v[194:195]
	v_and_b32_e32 v194, 0xffff0000, v190
	v_lshlrev_b32_e32 v195, 16, v190
	v_and_b32_e32 v190, 0xffff0000, v191
	v_lshlrev_b32_e32 v191, 16, v191
	v_pk_add_f32 v[14:15], v[14:15], v[190:191]
	v_and_b32_e32 v190, 0xffff0000, v192
	v_lshlrev_b32_e32 v191, 16, v192
	v_pk_add_f32 v[12:13], v[12:13], v[190:191]
	v_and_b32_e32 v190, 0xffff0000, v193
	v_lshlrev_b32_e32 v191, 16, v193
	v_pk_add_f32 v[10:11], v[10:11], v[190:191]
	v_and_b32_e32 v190, 0xffff0000, v186
	v_lshlrev_b32_e32 v191, 16, v186
	v_and_b32_e32 v186, 0xffff0000, v187
	v_lshlrev_b32_e32 v187, 16, v187
	v_pk_add_f32 v[6:7], v[6:7], v[186:187]
	v_and_b32_e32 v186, 0xffff0000, v188
	v_lshlrev_b32_e32 v187, 16, v188
	v_pk_add_f32 v[4:5], v[4:5], v[186:187]
	v_and_b32_e32 v186, 0xffff0000, v189
	v_lshlrev_b32_e32 v187, 16, v189
	v_pk_add_f32 v[56:57], v[56:57], v[202:203]
	v_pk_add_f32 v[48:49], v[48:49], v[198:199]
	v_pk_add_f32 v[16:17], v[16:17], v[194:195]
	v_pk_add_f32 v[8:9], v[8:9], v[190:191]
	v_pk_add_f32 v[2:3], v[2:3], v[186:187]
	s_mov_b64 exec, s[2:3]
	v_add_u32_e32 v61, 1, v61
	s_branch .Lpool4_loop
; __device__ __forceinline__ float lo16(unsigned w) { return __uint_as_float(w << 16); }
; __device__ __forceinline__ float hi16(unsigned w) { return __uint_as_float(w & 0xffff0000u); }
; __device__ __forceinline__ void prep_pool_item(const KPD& kp, int l, int sc, unsigned char* lds, int tid, int lane, int wave) {
;     ...
;       for (int j = lo; j < hi; ++j) { const bf16* up = P + (size_t)(rowbase + j - s0) * INP + cb;
; #pragma unroll
;           for (int q = 0; q < 4; ++q) { const v4u v = *(const v4u*)(up + 8 * q);
;               acc[8 * q] += lo16(v.x); acc[8 * q + 1] += hi16(v.x); acc[8 * q + 2] += lo16(v.y); acc[8 * q + 3] += hi16(v.y); acc[8 * q + 4] += lo16(v.z); acc[8 * q + 5] += hi16(v.z); acc[8 * q + 6] += lo16(v.w); acc[8 * q + 7] += hi16(v.w); } }
;       const float rc = 1.0f / (float)(hi - lo);
.Lpool4_done:
	s_mov_b64 exec, s[2:3]
	s_waitcnt vmcnt(0)
	s_or_b64 exec, exec, s[2:3]
	s_branch .LBB0_255

;     __device__ __forceinline__ unsigned char* ws() const { return (unsigned char*)(__attribute__((address_space(1))) unsigned char*)ld(23); }
; #define GRIDBAR() do { XcdBarrier b_; b_.bar = (unsigned*)kp.ws() + 1024; b_.x = xb_xcc_id(); b_.st = (volatile LAS unsigned*)(lds + CTRL_OFF) + 8; xcd_barrier(b_); } while (0)
; __global__ void __launch_bounds__(512, 2) fwd_kernel(KP kparg) {
;     ...
;         if (l == 0 && c < 64) { const int j = c >> 2, sl = c & 3; const int k0 = (sl == 0 ? 0 : sl == 1 ? 12 : sl == 2 ? 24 : 34) * 64, kl = (sl < 2 ? 12 : 10) * 64;
;             pg8::Gemm g{ACT + (size_t)MLAT * DFF + k0, (const bf16*)(ws + WS_WDN) + k0, MCTX, D, kl, DFF}; pg8::OneUnit S{j >> 2, j & 3};
;             pg8::EpiPart E{(float*)(ws + WS_PART) + (size_t)sl * MCTX * D, mod + 5120 + 4 * 6144};
;             pg8::gemm_phase<pg8::EpiPart, pg8::OneUnit, true, true>(ldsg, g, S, E); }
;         GRIDBAR();
;     }
.LBB0_1014:
	v_readlane_b32 s0, v254, 63
	v_readlane_b32 s1, v255, 0
	s_and_b64 vcc, exec, s[0:1]
	s_cbranch_vccz .Lnot_last_layer
	s_endpgm
